# P0 weight-transpose items: gain loads into own registers, per-chunk vmcnt(0) chain removed, 16 multiplies after one wait (16 loads in flight per item)
# speedup vs baseline: 1.0021x; 1.0021x over previous
.LBB0_6:
	s_add_i32 s34, s54, 0xfffff500
	s_cmpk_lt_u32 s34, 0xb00
	s_cselect_b64 s[0:1], -1, 0
	s_add_i32 s35, s54, 0xffffe480
	s_cmpk_lt_u32 s35, 0x580
	s_cselect_b64 s[2:3], -1, 0
	s_or_b64 s[0:1], s[0:1], s[2:3]
	s_cmpk_gt_i32 s54, 0x2abf
	s_cselect_b64 s[2:3], -1, 0
	s_or_b64 s[0:1], s[2:3], s[0:1]
	s_and_b64 vcc, exec, s[0:1]
	s_cbranch_vccnz .LBB0_5
	s_cmpk_gt_i32 s54, 0x15ff
	s_mov_b64 s[0:1], -1
	s_cbranch_scc0 .LBB0_115
	s_cmpk_gt_u32 s54, 0x20ff
	s_cbranch_scc0 .LBB0_112
	s_cmpk_gt_u32 s54, 0x287f
	s_cbranch_scc0 .LBB0_74
	s_cmpk_gt_u32 s54, 0x297f
	s_cbranch_scc0 .LBB0_55
	s_cmpk_gt_u32 s54, 0x2a3f
	s_cbranch_scc0 .LBB0_29
	s_cmpk_gt_u32 s54, 0x2a7f
	s_cselect_b64 s[2:3], -1, 0
	s_and_b64 s[0:1], s[2:3], exec
	s_cselect_b32 s1, s46, 0xffffd5c0
	s_cselect_b32 s0, 64, 0
	s_add_i32 s1, s1, s54
	s_lshl_b32 s29, s1, 5
	s_and_b32 s22, s29, 32
	s_lshl_b32 s28, s1, 6
	s_and_b32 s28, s28, 0x380
	s_or_b32 s0, s22, s0
	s_lshl_b32 s1, s1, 2
	s_or_b32 s0, s0, s28
	s_and_b32 s28, s1, 0x7fffffc0
	v_or_b32_e32 v36, s28, v35
	s_lshl_b32 s22, s0, 2
	v_lshl_add_u64 v[30:31], v[38:39], 0, s[22:23]
	v_lshlrev_b64 v[2:3], 12, v[36:37]
	v_lshl_add_u64 v[2:3], v[30:31], 0, v[2:3]
	global_load_dwordx4 v[2:5], v[2:3], off
	v_cmp_ne_u32_e64 s[0:1], 1, v62
	s_andn2_b64 vcc, exec, s[14:15]
	v_lshl_add_u64 v[52:53], v[36:37], 2, s[12:13]
	s_cbranch_vccnz .LBB0_14
	global_load_dword v96, v[52:53], off
.LBB0_14:
	v_or_b32_e32 v6, 8, v36
	v_mov_b32_e32 v7, v37
	v_lshlrev_b64 v[6:7], 12, v[6:7]
	v_lshl_add_u64 v[6:7], v[30:31], 0, v[6:7]
	global_load_dwordx4 v[6:9], v[6:7], off
	s_and_b64 vcc, exec, s[0:1]
	s_cbranch_vccnz .LBB0_16
	global_load_dword v98, v[52:53], off offset:32
.LBB0_16:
	v_or_b32_e32 v10, 16, v36
	v_mov_b32_e32 v11, v37
	v_lshlrev_b64 v[10:11], 12, v[10:11]
	v_lshl_add_u64 v[10:11], v[30:31], 0, v[10:11]
	global_load_dwordx4 v[10:13], v[10:11], off
	s_and_b64 vcc, exec, s[0:1]
	s_cbranch_vccnz .LBB0_18
	global_load_dword v100, v[52:53], off offset:64
.LBB0_18:
	v_or_b32_e32 v14, 24, v36
	v_mov_b32_e32 v15, v37
	v_lshlrev_b64 v[14:15], 12, v[14:15]
	v_lshl_add_u64 v[14:15], v[30:31], 0, v[14:15]
	global_load_dwordx4 v[14:17], v[14:15], off
	s_and_b64 vcc, exec, s[0:1]
	s_cbranch_vccnz .LBB0_20
	global_load_dword v102, v[52:53], off offset:96
.LBB0_20:
	v_or_b32_e32 v18, 32, v36
	v_mov_b32_e32 v19, v37
	v_lshlrev_b64 v[18:19], 12, v[18:19]
	v_lshl_add_u64 v[18:19], v[30:31], 0, v[18:19]
	global_load_dwordx4 v[18:21], v[18:19], off
	s_and_b64 vcc, exec, s[0:1]
	s_cbranch_vccnz .LBB0_22
	global_load_dword v104, v[52:53], off offset:128
.LBB0_22:
	v_or_b32_e32 v22, 40, v36
	v_mov_b32_e32 v23, v37
	v_lshlrev_b64 v[22:23], 12, v[22:23]
	v_lshl_add_u64 v[22:23], v[30:31], 0, v[22:23]
	global_load_dwordx4 v[22:25], v[22:23], off
	s_and_b64 vcc, exec, s[0:1]
	s_cbranch_vccnz .LBB0_24
	global_load_dword v106, v[52:53], off offset:160
.LBB0_24:
	v_or_b32_e32 v26, 48, v36
	v_mov_b32_e32 v27, v37
	v_lshlrev_b64 v[26:27], 12, v[26:27]
	v_lshl_add_u64 v[26:27], v[30:31], 0, v[26:27]
	global_load_dwordx4 v[26:29], v[26:27], off
	s_and_b64 vcc, exec, s[0:1]
	s_cbranch_vccnz .LBB0_26
	global_load_dword v108, v[52:53], off offset:192
.LBB0_26:
	v_or_b32_e32 v36, 56, v36
	v_lshlrev_b64 v[32:33], 12, v[36:37]
	v_lshl_add_u64 v[30:31], v[30:31], 0, v[32:33]
	global_load_dwordx4 v[30:33], v[30:31], off
	s_and_b64 vcc, exec, s[0:1]
	s_cbranch_vccnz .LBB0_28
	global_load_dword v110, v[52:53], off offset:224
	s_waitcnt vmcnt(0)
	v_pk_mul_f32 v[4:5], v[4:5], v[96:97] op_sel_hi:[1,0]
	v_pk_mul_f32 v[2:3], v[2:3], v[96:97] op_sel_hi:[1,0]
	v_pk_mul_f32 v[8:9], v[8:9], v[98:99] op_sel_hi:[1,0]
	v_pk_mul_f32 v[6:7], v[6:7], v[98:99] op_sel_hi:[1,0]
	v_pk_mul_f32 v[12:13], v[12:13], v[100:101] op_sel_hi:[1,0]
	v_pk_mul_f32 v[10:11], v[10:11], v[100:101] op_sel_hi:[1,0]
	v_pk_mul_f32 v[16:17], v[16:17], v[102:103] op_sel_hi:[1,0]
	v_pk_mul_f32 v[14:15], v[14:15], v[102:103] op_sel_hi:[1,0]
	v_pk_mul_f32 v[20:21], v[20:21], v[104:105] op_sel_hi:[1,0]
	v_pk_mul_f32 v[18:19], v[18:19], v[104:105] op_sel_hi:[1,0]
	v_pk_mul_f32 v[24:25], v[24:25], v[106:107] op_sel_hi:[1,0]
	v_pk_mul_f32 v[22:23], v[22:23], v[106:107] op_sel_hi:[1,0]
	v_pk_mul_f32 v[28:29], v[28:29], v[108:109] op_sel_hi:[1,0]
	v_pk_mul_f32 v[26:27], v[26:27], v[108:109] op_sel_hi:[1,0]
	v_pk_mul_f32 v[32:33], v[32:33], v[110:111] op_sel_hi:[1,0]
	v_pk_mul_f32 v[30:31], v[30:31], v[110:111] op_sel_hi:[1,0]

.LBB0_29:
	s_and_b64 vcc, exec, s[0:1]
	s_cbranch_vccz .LBB0_143
	s_bfe_u32 s1, s40, 0x30007
	s_and_b32 s0, s40, 0x60
	s_mulk_i32 s1, 0x60
	s_add_i32 s1, s1, s0
	s_cmpk_lg_i32 s0, 0x60
	s_cselect_b32 s22, s1, -1
	s_and_b32 s0, s42, 0x7fc0
	s_add_i32 s28, s0, 0xffffad00
	s_cmp_gt_i32 s22, -1
	v_cndmask_b32_e64 v3, 0, 1, s[10:11]
	s_cselect_b64 s[30:31], -1, 0
	s_cmp_lt_i32 s22, 0
	v_or_b32_e32 v36, s28, v35
	v_lshl_add_u64 v[52:53], s[22:23], 2, v[42:43]
	v_mov_b32_e32 v2, 0
	v_cmp_ne_u32_e64 s[0:1], 1, v3
	v_mov_b32_e32 v6, 0
	v_mov_b32_e32 v7, 0
	v_mov_b32_e32 v8, 0
	v_mov_b32_e32 v9, 0
	s_cbranch_scc1 .LBB0_33
	v_mad_u64_u32 v[4:5], s[2:3], v36, s48, v[52:53]
	global_load_dwordx4 v[6:9], v[4:5], off
	s_and_b64 vcc, exec, s[0:1]
	s_cbranch_vccnz .LBB0_33
	v_lshl_add_u64 v[4:5], v[36:37], 2, s[8:9]
	global_load_dword v96, v[4:5], off
.LBB0_33:
	v_cndmask_b32_e64 v3, 0, 1, s[30:31]
	v_cmp_ne_u32_e64 s[2:3], 1, v3
	s_andn2_b64 vcc, exec, s[30:31]
	v_mov_b32_e32 v3, 0
	v_mov_b32_e32 v4, 0
	v_mov_b32_e32 v5, 0
	s_cbranch_vccnz .LBB0_36
	v_or_b32_e32 v2, 8, v36
	v_mad_u64_u32 v[2:3], s[30:31], v2, s48, v[52:53]
	global_load_dwordx4 v[2:5], v[2:3], off
	s_and_b64 vcc, exec, s[0:1]
	s_cbranch_vccnz .LBB0_36
	v_lshl_add_u64 v[10:11], v[36:37], 2, s[8:9]
	global_load_dword v98, v[10:11], off offset:32
.LBB0_36:
	v_mov_b32_e32 v10, 0
	s_and_b64 vcc, exec, s[2:3]
	v_mov_b32_e32 v14, 0
	v_mov_b32_e32 v15, 0
	v_mov_b32_e32 v16, 0
	v_mov_b32_e32 v17, 0
	s_cbranch_vccnz .LBB0_39
	v_or_b32_e32 v11, 16, v36
	v_mad_u64_u32 v[12:13], s[30:31], v11, s48, v[52:53]
	global_load_dwordx4 v[14:17], v[12:13], off
	s_and_b64 vcc, exec, s[0:1]
	s_cbranch_vccnz .LBB0_39
	v_lshl_add_u64 v[12:13], v[36:37], 2, s[8:9]
	global_load_dword v100, v[12:13], off offset:64
.LBB0_39:
	s_and_b64 vcc, exec, s[2:3]
	v_mov_b32_e32 v11, 0
	v_mov_b32_e32 v12, 0
	v_mov_b32_e32 v13, 0
	s_cbranch_vccnz .LBB0_42
	v_or_b32_e32 v10, 24, v36
	v_mad_u64_u32 v[10:11], s[30:31], v10, s48, v[52:53]
	global_load_dwordx4 v[10:13], v[10:11], off
	s_and_b64 vcc, exec, s[0:1]
	s_cbranch_vccnz .LBB0_42
	v_lshl_add_u64 v[18:19], v[36:37], 2, s[8:9]
	global_load_dword v102, v[18:19], off offset:96
.LBB0_42:
	v_mov_b32_e32 v18, 0
	s_and_b64 vcc, exec, s[2:3]
	v_mov_b32_e32 v22, 0
	v_mov_b32_e32 v23, 0
	v_mov_b32_e32 v24, 0
	v_mov_b32_e32 v25, 0
	s_cbranch_vccnz .LBB0_45
	v_or_b32_e32 v19, 32, v36
	v_mad_u64_u32 v[20:21], s[30:31], v19, s48, v[52:53]
	global_load_dwordx4 v[22:25], v[20:21], off
	s_and_b64 vcc, exec, s[0:1]
	s_cbranch_vccnz .LBB0_45
	v_lshl_add_u64 v[20:21], v[36:37], 2, s[8:9]
	global_load_dword v104, v[20:21], off offset:128
.LBB0_45:
	s_and_b64 vcc, exec, s[2:3]
	v_mov_b32_e32 v19, 0
	v_mov_b32_e32 v20, 0
	v_mov_b32_e32 v21, 0
	s_cbranch_vccnz .LBB0_48
	v_or_b32_e32 v18, 40, v36
	v_mad_u64_u32 v[18:19], s[30:31], v18, s48, v[52:53]
	global_load_dwordx4 v[18:21], v[18:19], off
	s_and_b64 vcc, exec, s[0:1]
	s_cbranch_vccnz .LBB0_48
	v_lshl_add_u64 v[26:27], v[36:37], 2, s[8:9]
	global_load_dword v106, v[26:27], off offset:160
.LBB0_48:
	v_mov_b32_e32 v26, 0
	s_and_b64 vcc, exec, s[2:3]
	v_mov_b32_e32 v30, 0
	v_mov_b32_e32 v31, 0
	v_mov_b32_e32 v32, 0
	v_mov_b32_e32 v33, 0
	s_cbranch_vccnz .LBB0_51
	v_or_b32_e32 v27, 48, v36
	v_mad_u64_u32 v[28:29], s[30:31], v27, s48, v[52:53]
	global_load_dwordx4 v[30:33], v[28:29], off
	s_and_b64 vcc, exec, s[0:1]
	s_cbranch_vccnz .LBB0_51
	v_lshl_add_u64 v[28:29], v[36:37], 2, s[8:9]
	global_load_dword v108, v[28:29], off offset:192
.LBB0_51:
	s_and_b64 vcc, exec, s[2:3]
	v_mov_b32_e32 v27, 0
	v_mov_b32_e32 v28, 0
	v_mov_b32_e32 v29, 0
	s_cbranch_vccnz .LBB0_54
	v_or_b32_e32 v26, 56, v36
	v_mad_u64_u32 v[26:27], s[2:3], v26, s48, v[52:53]
	global_load_dwordx4 v[26:29], v[26:27], off
	s_and_b64 vcc, exec, s[0:1]
	s_cbranch_vccnz .LBB0_54
	v_lshl_add_u64 v[52:53], v[36:37], 2, s[8:9]
	global_load_dword v110, v[52:53], off offset:224
	s_waitcnt vmcnt(0)
	v_pk_mul_f32 v[8:9], v[8:9], v[96:97] op_sel_hi:[1,0]
	v_pk_mul_f32 v[6:7], v[6:7], v[96:97] op_sel_hi:[1,0]
	v_pk_mul_f32 v[4:5], v[4:5], v[98:99] op_sel_hi:[1,0]
	v_pk_mul_f32 v[2:3], v[2:3], v[98:99] op_sel_hi:[1,0]
	v_pk_mul_f32 v[16:17], v[16:17], v[100:101] op_sel_hi:[1,0]
	v_pk_mul_f32 v[14:15], v[14:15], v[100:101] op_sel_hi:[1,0]
	v_pk_mul_f32 v[12:13], v[12:13], v[102:103] op_sel_hi:[1,0]
	v_pk_mul_f32 v[10:11], v[10:11], v[102:103] op_sel_hi:[1,0]
	v_pk_mul_f32 v[24:25], v[24:25], v[104:105] op_sel_hi:[1,0]
	v_pk_mul_f32 v[22:23], v[22:23], v[104:105] op_sel_hi:[1,0]
	v_pk_mul_f32 v[20:21], v[20:21], v[106:107] op_sel_hi:[1,0]
	v_pk_mul_f32 v[18:19], v[18:19], v[106:107] op_sel_hi:[1,0]
	v_pk_mul_f32 v[32:33], v[32:33], v[108:109] op_sel_hi:[1,0]
	v_pk_mul_f32 v[30:31], v[30:31], v[108:109] op_sel_hi:[1,0]
	v_pk_mul_f32 v[28:29], v[28:29], v[110:111] op_sel_hi:[1,0]
	v_pk_mul_f32 v[26:27], v[26:27], v[110:111] op_sel_hi:[1,0]

.LBB0_56:
	s_and_b32 s2, s40, 0x1e0
	s_and_b32 s0, s44, 0xffc0
	s_add_i32 s22, s0, 0xffff5e00
	s_lshl_b32 s0, s2, 2
	s_add_u32 s0, s6, s0
	s_addc_u32 s1, s7, 0
	v_lshlrev_b32_e32 v36, 2, v34
	v_lshl_add_u64 v[2:3], s[0:1], 0, v[36:37]
	v_or_b32_e32 v6, s22, v35
	v_lshl_add_u64 v[30:31], v[2:3], 0, s[26:27]
	v_mad_u64_u32 v[2:3], s[0:1], v6, s49, v[30:31]
	global_load_dwordx4 v[2:5], v[2:3], off
	v_mov_b32_e32 v36, v6
	v_cndmask_b32_e64 v6, 0, 1, s[24:25]
	v_cmp_ne_u32_e64 s[0:1], 1, v6
	s_andn2_b64 vcc, exec, s[24:25]
	v_lshl_add_u64 v[52:53], v[36:37], 2, s[4:5]
	s_cbranch_vccnz .LBB0_58
	global_load_dword v96, v[52:53], off
.LBB0_58:
	v_or_b32_e32 v6, 8, v36
	v_mad_u64_u32 v[6:7], s[28:29], v6, s49, v[30:31]
	global_load_dwordx4 v[6:9], v[6:7], off
	s_and_b64 vcc, exec, s[0:1]
	s_cbranch_vccnz .LBB0_60
	global_load_dword v98, v[52:53], off offset:32
.LBB0_60:
	v_or_b32_e32 v10, 16, v36
	v_mad_u64_u32 v[10:11], s[28:29], v10, s49, v[30:31]
	global_load_dwordx4 v[10:13], v[10:11], off
	s_and_b64 vcc, exec, s[0:1]
	s_cbranch_vccnz .LBB0_62
	global_load_dword v100, v[52:53], off offset:64
.LBB0_62:
	v_or_b32_e32 v14, 24, v36
	v_mad_u64_u32 v[14:15], s[28:29], v14, s49, v[30:31]
	global_load_dwordx4 v[14:17], v[14:15], off
	s_and_b64 vcc, exec, s[0:1]
	s_cbranch_vccnz .LBB0_64
	global_load_dword v102, v[52:53], off offset:96
.LBB0_64:
	v_or_b32_e32 v18, 32, v36
	v_mad_u64_u32 v[18:19], s[28:29], v18, s49, v[30:31]
	global_load_dwordx4 v[18:21], v[18:19], off
	s_and_b64 vcc, exec, s[0:1]
	s_cbranch_vccnz .LBB0_66
	global_load_dword v104, v[52:53], off offset:128
.LBB0_66:
	v_or_b32_e32 v22, 40, v36
	v_mad_u64_u32 v[22:23], s[28:29], v22, s49, v[30:31]
	global_load_dwordx4 v[22:25], v[22:23], off
	s_and_b64 vcc, exec, s[0:1]
	s_cbranch_vccnz .LBB0_68
	global_load_dword v106, v[52:53], off offset:160
.LBB0_68:
	v_or_b32_e32 v26, 48, v36
	v_mad_u64_u32 v[26:27], s[28:29], v26, s49, v[30:31]
	global_load_dwordx4 v[26:29], v[26:27], off
	s_and_b64 vcc, exec, s[0:1]
	s_cbranch_vccnz .LBB0_70
	global_load_dword v108, v[52:53], off offset:192
.LBB0_70:
	v_or_b32_e32 v32, 56, v36
	v_mad_u64_u32 v[30:31], s[28:29], v32, s49, v[30:31]
	global_load_dwordx4 v[30:33], v[30:31], off
	s_and_b64 vcc, exec, s[0:1]
	s_cbranch_vccnz .LBB0_72
	global_load_dword v110, v[52:53], off offset:224
	s_waitcnt vmcnt(0)
	v_pk_mul_f32 v[4:5], v[4:5], v[96:97] op_sel_hi:[1,0]
	v_pk_mul_f32 v[2:3], v[2:3], v[96:97] op_sel_hi:[1,0]
	v_pk_mul_f32 v[8:9], v[8:9], v[98:99] op_sel_hi:[1,0]
	v_pk_mul_f32 v[6:7], v[6:7], v[98:99] op_sel_hi:[1,0]
	v_pk_mul_f32 v[12:13], v[12:13], v[100:101] op_sel_hi:[1,0]
	v_pk_mul_f32 v[10:11], v[10:11], v[100:101] op_sel_hi:[1,0]
	v_pk_mul_f32 v[16:17], v[16:17], v[102:103] op_sel_hi:[1,0]
	v_pk_mul_f32 v[14:15], v[14:15], v[102:103] op_sel_hi:[1,0]
	v_pk_mul_f32 v[20:21], v[20:21], v[104:105] op_sel_hi:[1,0]
	v_pk_mul_f32 v[18:19], v[18:19], v[104:105] op_sel_hi:[1,0]
	v_pk_mul_f32 v[24:25], v[24:25], v[106:107] op_sel_hi:[1,0]
	v_pk_mul_f32 v[22:23], v[22:23], v[106:107] op_sel_hi:[1,0]
	v_pk_mul_f32 v[28:29], v[28:29], v[108:109] op_sel_hi:[1,0]
	v_pk_mul_f32 v[26:27], v[26:27], v[108:109] op_sel_hi:[1,0]
	v_pk_mul_f32 v[32:33], v[32:33], v[110:111] op_sel_hi:[1,0]
	v_pk_mul_f32 v[30:31], v[30:31], v[110:111] op_sel_hi:[1,0]

.LBB0_86:
	s_lshl_b32 s31, s2, 6
	s_and_b32 s0, s31, 0xffc0
	s_cmp_gt_i32 s22, -1
	v_cndmask_b32_e64 v3, 0, 1, s[24:25]
	s_cselect_b64 s[28:29], -1, 0
	s_cmp_lt_i32 s22, 0
	v_or_b32_e32 v36, s0, v35
	v_lshl_add_u64 v[52:53], s[22:23], 2, v[48:49]
	v_mov_b32_e32 v2, 0
	v_cmp_ne_u32_e64 s[0:1], 1, v3
	v_mov_b32_e32 v6, 0
	v_mov_b32_e32 v7, 0
	v_mov_b32_e32 v8, 0
	v_mov_b32_e32 v9, 0
	s_cbranch_scc1 .LBB0_89
	v_mad_u64_u32 v[4:5], s[2:3], v36, s49, v[52:53]
	global_load_dwordx4 v[6:9], v[4:5], off
	s_and_b64 vcc, exec, s[0:1]
	s_cbranch_vccnz .LBB0_89
	v_lshlrev_b32_e32 v3, 2, v36
	global_load_dword v96, v3, s[4:5]
.LBB0_89:
	v_cndmask_b32_e64 v3, 0, 1, s[28:29]
	v_cmp_ne_u32_e64 s[2:3], 1, v3
	s_andn2_b64 vcc, exec, s[28:29]
	v_mov_b32_e32 v3, 0
	v_mov_b32_e32 v4, 0
	v_mov_b32_e32 v5, 0
	s_cbranch_vccnz .LBB0_92
	v_or_b32_e32 v2, 8, v36
	v_mad_u64_u32 v[2:3], s[28:29], v2, s49, v[52:53]
	global_load_dwordx4 v[2:5], v[2:3], off
	s_and_b64 vcc, exec, s[0:1]
	s_cbranch_vccnz .LBB0_92
	v_lshlrev_b32_e32 v10, 2, v36
	global_load_dword v98, v10, s[4:5] offset:32
.LBB0_92:
	v_mov_b32_e32 v10, 0
	s_and_b64 vcc, exec, s[2:3]
	v_mov_b32_e32 v14, 0
	v_mov_b32_e32 v15, 0
	v_mov_b32_e32 v16, 0
	v_mov_b32_e32 v17, 0
	s_cbranch_vccnz .LBB0_95
	v_or_b32_e32 v11, 16, v36
	v_mad_u64_u32 v[12:13], s[28:29], v11, s49, v[52:53]
	global_load_dwordx4 v[14:17], v[12:13], off
	s_and_b64 vcc, exec, s[0:1]
	s_cbranch_vccnz .LBB0_95
	v_lshlrev_b32_e32 v11, 2, v36
	global_load_dword v100, v11, s[4:5] offset:64
.LBB0_95:
	s_and_b64 vcc, exec, s[2:3]
	v_mov_b32_e32 v11, 0
	v_mov_b32_e32 v12, 0
	v_mov_b32_e32 v13, 0
	s_cbranch_vccnz .LBB0_98
	v_or_b32_e32 v10, 24, v36
	v_mad_u64_u32 v[10:11], s[28:29], v10, s49, v[52:53]
	global_load_dwordx4 v[10:13], v[10:11], off
	s_and_b64 vcc, exec, s[0:1]
	s_cbranch_vccnz .LBB0_98
	v_lshlrev_b32_e32 v18, 2, v36
	global_load_dword v102, v18, s[4:5] offset:96
.LBB0_98:
	v_mov_b32_e32 v18, 0
	s_and_b64 vcc, exec, s[2:3]
	v_mov_b32_e32 v22, 0
	v_mov_b32_e32 v23, 0
	v_mov_b32_e32 v24, 0
	v_mov_b32_e32 v25, 0
	s_cbranch_vccnz .LBB0_101
	v_or_b32_e32 v19, 32, v36
	v_mad_u64_u32 v[20:21], s[28:29], v19, s49, v[52:53]
	global_load_dwordx4 v[22:25], v[20:21], off
	s_and_b64 vcc, exec, s[0:1]
	s_cbranch_vccnz .LBB0_101
	v_lshlrev_b32_e32 v19, 2, v36
	global_load_dword v104, v19, s[4:5] offset:128
.LBB0_101:
	s_and_b64 vcc, exec, s[2:3]
	v_mov_b32_e32 v19, 0
	v_mov_b32_e32 v20, 0
	v_mov_b32_e32 v21, 0
	s_cbranch_vccnz .LBB0_104
	v_or_b32_e32 v18, 40, v36
	v_mad_u64_u32 v[18:19], s[28:29], v18, s49, v[52:53]
	global_load_dwordx4 v[18:21], v[18:19], off
	s_and_b64 vcc, exec, s[0:1]
	s_cbranch_vccnz .LBB0_104
	v_lshlrev_b32_e32 v26, 2, v36
	global_load_dword v106, v26, s[4:5] offset:160
.LBB0_104:
	v_mov_b32_e32 v26, 0
	s_and_b64 vcc, exec, s[2:3]
	v_mov_b32_e32 v30, 0
	v_mov_b32_e32 v31, 0
	v_mov_b32_e32 v32, 0
	v_mov_b32_e32 v33, 0
	s_cbranch_vccnz .LBB0_107
	v_or_b32_e32 v27, 48, v36
	v_mad_u64_u32 v[28:29], s[28:29], v27, s49, v[52:53]
	global_load_dwordx4 v[30:33], v[28:29], off
	s_and_b64 vcc, exec, s[0:1]
	s_cbranch_vccnz .LBB0_107
	v_lshlrev_b32_e32 v27, 2, v36
	global_load_dword v108, v27, s[4:5] offset:192
.LBB0_107:
	s_and_b64 vcc, exec, s[2:3]
	v_mov_b32_e32 v27, 0
	v_mov_b32_e32 v28, 0
	v_mov_b32_e32 v29, 0
	s_cbranch_vccnz .LBB0_110
	v_or_b32_e32 v26, 56, v36
	v_mad_u64_u32 v[26:27], s[2:3], v26, s49, v[52:53]
	global_load_dwordx4 v[26:29], v[26:27], off
	s_and_b64 vcc, exec, s[0:1]
	s_cbranch_vccnz .LBB0_110
	v_lshlrev_b32_e32 v36, 2, v36
	global_load_dword v110, v36, s[4:5] offset:224
	s_waitcnt vmcnt(0)
	v_pk_mul_f32 v[8:9], v[8:9], v[96:97] op_sel_hi:[1,0]
	v_pk_mul_f32 v[6:7], v[6:7], v[96:97] op_sel_hi:[1,0]
	v_pk_mul_f32 v[4:5], v[4:5], v[98:99] op_sel_hi:[1,0]
	v_pk_mul_f32 v[2:3], v[2:3], v[98:99] op_sel_hi:[1,0]
	v_pk_mul_f32 v[16:17], v[16:17], v[100:101] op_sel_hi:[1,0]
	v_pk_mul_f32 v[14:15], v[14:15], v[100:101] op_sel_hi:[1,0]
	v_pk_mul_f32 v[12:13], v[12:13], v[102:103] op_sel_hi:[1,0]
	v_pk_mul_f32 v[10:11], v[10:11], v[102:103] op_sel_hi:[1,0]
	v_pk_mul_f32 v[24:25], v[24:25], v[104:105] op_sel_hi:[1,0]
	v_pk_mul_f32 v[22:23], v[22:23], v[104:105] op_sel_hi:[1,0]
	v_pk_mul_f32 v[20:21], v[20:21], v[106:107] op_sel_hi:[1,0]
	v_pk_mul_f32 v[18:19], v[18:19], v[106:107] op_sel_hi:[1,0]
	v_pk_mul_f32 v[32:33], v[32:33], v[108:109] op_sel_hi:[1,0]
	v_pk_mul_f32 v[30:31], v[30:31], v[108:109] op_sel_hi:[1,0]
	v_pk_mul_f32 v[28:29], v[28:29], v[110:111] op_sel_hi:[1,0]
	v_pk_mul_f32 v[26:27], v[26:27], v[110:111] op_sel_hi:[1,0]

.LBB0_119:
	s_mul_hi_i32 s1, s34, 0x2e8ba2e9
	s_lshr_b32 s3, s1, 31
	s_ashr_i32 s1, s1, 5
	s_add_i32 s3, s1, s3
	s_mul_i32 s1, s3, 0xb0
	s_sub_i32 s29, s34, s1
	s_bfe_u32 s1, s29, 0x10002
	s_add_i32 s1, s1, s2
	s_lshl_b32 s1, s1, 3
	s_lshl_b32 s2, s0, 3
	s_lshl_b32 s31, s29, 5
	s_load_dwordx2 s[0:1], s[80:81], s1 offset:0x0
	s_nop 0
	s_load_dwordx2 s[34:35], s[80:81], s2 offset:0x0
	s_lshl_b32 s2, s29, 4
	s_and_b32 s22, s31, 0x60
	s_and_b32 s2, s2, 0xffffff80
	s_or_b32 s22, s2, s22
	s_lshl_b32 s28, s3, 6
	s_cmp_gt_i32 s29, -1
	s_cselect_b64 s[36:37], -1, 0
	s_lshl_b64 s[2:3], s[22:23], 2
	s_waitcnt lgkmcnt(0)
	s_add_u32 s0, s0, s2
	s_addc_u32 s1, s1, s3
	s_cmp_lg_u64 s[34:35], 0
	s_cselect_b64 s[2:3], -1, 0
	v_or_b32_e32 v52, s28, v35
	v_lshlrev_b32_e32 v36, 2, v34
	v_cndmask_b32_e64 v3, 0, 1, s[2:3]
	s_cmp_lt_i32 s29, 0
	v_lshl_add_u64 v[54:55], s[0:1], 0, v[36:37]
	v_mov_b32_e32 v2, 0
	v_ashrrev_i32_e32 v53, 31, v52
	v_cmp_ne_u32_e64 s[0:1], 1, v3
	v_mov_b32_e32 v6, 0
	v_mov_b32_e32 v7, 0
	v_mov_b32_e32 v8, 0
	v_mov_b32_e32 v9, 0
	s_cbranch_scc1 .LBB0_122
	v_mad_i64_i32 v[4:5], s[2:3], v52, s53, v[54:55]
	global_load_dwordx4 v[6:9], v[4:5], off
	s_and_b64 vcc, exec, s[0:1]
	s_cbranch_vccnz .LBB0_122
	v_lshl_add_u64 v[4:5], v[52:53], 2, s[34:35]
	global_load_dword v96, v[4:5], off
.LBB0_122:
	v_cndmask_b32_e64 v3, 0, 1, s[36:37]
	v_cmp_ne_u32_e64 s[2:3], 1, v3
	s_andn2_b64 vcc, exec, s[36:37]
	v_mov_b32_e32 v3, 0
	v_mov_b32_e32 v4, 0
	v_mov_b32_e32 v5, 0
	s_cbranch_vccnz .LBB0_125
	v_or_b32_e32 v2, 8, v52
	v_mad_i64_i32 v[2:3], s[36:37], v2, s53, v[54:55]
	global_load_dwordx4 v[2:5], v[2:3], off
	s_and_b64 vcc, exec, s[0:1]
	s_cbranch_vccnz .LBB0_125
	v_lshl_add_u64 v[10:11], v[52:53], 2, s[34:35]
	global_load_dword v98, v[10:11], off offset:32
.LBB0_125:
	v_mov_b32_e32 v10, 0
	s_and_b64 vcc, exec, s[2:3]
	v_mov_b32_e32 v14, 0
	v_mov_b32_e32 v15, 0
	v_mov_b32_e32 v16, 0
	v_mov_b32_e32 v17, 0
	s_cbranch_vccnz .LBB0_128
	v_or_b32_e32 v11, 16, v52
	v_mad_i64_i32 v[12:13], s[36:37], v11, s53, v[54:55]
	global_load_dwordx4 v[14:17], v[12:13], off
	s_and_b64 vcc, exec, s[0:1]
	s_cbranch_vccnz .LBB0_128
	v_lshl_add_u64 v[12:13], v[52:53], 2, s[34:35]
	global_load_dword v100, v[12:13], off offset:64
.LBB0_128:
	s_and_b64 vcc, exec, s[2:3]
	v_mov_b32_e32 v11, 0
	v_mov_b32_e32 v12, 0
	v_mov_b32_e32 v13, 0
	s_cbranch_vccnz .LBB0_131
	v_or_b32_e32 v10, 24, v52
	v_mad_i64_i32 v[10:11], s[36:37], v10, s53, v[54:55]
	global_load_dwordx4 v[10:13], v[10:11], off
	s_and_b64 vcc, exec, s[0:1]
	s_cbranch_vccnz .LBB0_131
	v_lshl_add_u64 v[18:19], v[52:53], 2, s[34:35]
	global_load_dword v102, v[18:19], off offset:96
.LBB0_131:
	v_mov_b32_e32 v18, 0
	s_and_b64 vcc, exec, s[2:3]
	v_mov_b32_e32 v22, 0
	v_mov_b32_e32 v23, 0
	v_mov_b32_e32 v24, 0
	v_mov_b32_e32 v25, 0
	s_cbranch_vccnz .LBB0_134
	v_or_b32_e32 v19, 32, v52
	v_mad_i64_i32 v[20:21], s[36:37], v19, s53, v[54:55]
	global_load_dwordx4 v[22:25], v[20:21], off
	s_and_b64 vcc, exec, s[0:1]
	s_cbranch_vccnz .LBB0_134
	v_lshl_add_u64 v[20:21], v[52:53], 2, s[34:35]
	global_load_dword v104, v[20:21], off offset:128
.LBB0_134:
	s_and_b64 vcc, exec, s[2:3]
	v_mov_b32_e32 v19, 0
	v_mov_b32_e32 v20, 0
	v_mov_b32_e32 v21, 0
	s_cbranch_vccnz .LBB0_137
	v_or_b32_e32 v18, 40, v52
	v_mad_i64_i32 v[18:19], s[36:37], v18, s53, v[54:55]
	global_load_dwordx4 v[18:21], v[18:19], off
	s_and_b64 vcc, exec, s[0:1]
	s_cbranch_vccnz .LBB0_137
	v_lshl_add_u64 v[26:27], v[52:53], 2, s[34:35]
	global_load_dword v106, v[26:27], off offset:160
.LBB0_137:
	v_mov_b32_e32 v26, 0
	s_and_b64 vcc, exec, s[2:3]
	v_mov_b32_e32 v30, 0
	v_mov_b32_e32 v31, 0
	v_mov_b32_e32 v32, 0
	v_mov_b32_e32 v33, 0
	s_cbranch_vccnz .LBB0_140
	v_or_b32_e32 v27, 48, v52
	v_mad_i64_i32 v[28:29], s[36:37], v27, s53, v[54:55]
	global_load_dwordx4 v[30:33], v[28:29], off
	s_and_b64 vcc, exec, s[0:1]
	s_cbranch_vccnz .LBB0_140
	v_lshl_add_u64 v[28:29], v[52:53], 2, s[34:35]
	global_load_dword v108, v[28:29], off offset:192
.LBB0_140:
	s_and_b64 vcc, exec, s[2:3]
	v_mov_b32_e32 v27, 0
	v_mov_b32_e32 v28, 0
	v_mov_b32_e32 v29, 0
	s_cbranch_vccnz .LBB0_4
	v_or_b32_e32 v26, 56, v52
	v_mad_i64_i32 v[26:27], s[2:3], v26, s53, v[54:55]
	global_load_dwordx4 v[26:29], v[26:27], off
	s_and_b64 vcc, exec, s[0:1]
	s_cbranch_vccnz .LBB0_4
	v_lshl_add_u64 v[52:53], v[52:53], 2, s[34:35]
	global_load_dword v110, v[52:53], off offset:224
	s_waitcnt vmcnt(0)
	v_pk_mul_f32 v[8:9], v[8:9], v[96:97] op_sel_hi:[1,0]
	v_pk_mul_f32 v[6:7], v[6:7], v[96:97] op_sel_hi:[1,0]
	v_pk_mul_f32 v[4:5], v[4:5], v[98:99] op_sel_hi:[1,0]
	v_pk_mul_f32 v[2:3], v[2:3], v[98:99] op_sel_hi:[1,0]
	v_pk_mul_f32 v[16:17], v[16:17], v[100:101] op_sel_hi:[1,0]
	v_pk_mul_f32 v[14:15], v[14:15], v[100:101] op_sel_hi:[1,0]
	v_pk_mul_f32 v[12:13], v[12:13], v[102:103] op_sel_hi:[1,0]
	v_pk_mul_f32 v[10:11], v[10:11], v[102:103] op_sel_hi:[1,0]
	v_pk_mul_f32 v[24:25], v[24:25], v[104:105] op_sel_hi:[1,0]
	v_pk_mul_f32 v[22:23], v[22:23], v[104:105] op_sel_hi:[1,0]
	v_pk_mul_f32 v[20:21], v[20:21], v[106:107] op_sel_hi:[1,0]
	v_pk_mul_f32 v[18:19], v[18:19], v[106:107] op_sel_hi:[1,0]
	v_pk_mul_f32 v[32:33], v[32:33], v[108:109] op_sel_hi:[1,0]
	v_pk_mul_f32 v[30:31], v[30:31], v[108:109] op_sel_hi:[1,0]
	v_pk_mul_f32 v[28:29], v[28:29], v[110:111] op_sel_hi:[1,0]
	v_pk_mul_f32 v[26:27], v[26:27], v[110:111] op_sel_hi:[1,0]
	s_branch .LBB0_4
